# attention: K LDS-DMA after the fourth QK MFMA pair, V LDS-DMA after the fourth PV MFMA group
# baseline (speedup 1.0000x reference)
; #define SBAR() __builtin_amdgcn_sched_barrier(0)
; #define VF_WAIT(N) do { asm volatile("s_waitcnt lgkmcnt(" #N ")" ::: "memory"); SBAR(); } while (0)
; #define A_WAITBAR(N) asm volatile("s_waitcnt vmcnt(" #N ") lgkmcnt(0) ; A256BAR\n\ts_barrier" ::: "memory")
; #define DMA_V(t, sl) do { const char* b_ = Vb + (size_t)(t) * TSTRIDE; const unsigned d_ = RFL(vdst + (sl) * 32768); glds16(b_ + voff[0], d_); glds16(b_ + voff[1], d_ + 1024); glds16(b_ + voff[2], d_ + 2048); glds16(b_ + voff[3], d_ + 3072); } while (0)
; __device__ __forceinline__ void pv8(f32x16* o, int vb, bf16x8 pa0, bf16x8 pa1, bf16x8 pa2, bf16x8 pa3) {
;   VFrag fa, fb; const int vb2 = vb + 16384;
;   vf_read<0>(fa, vb);
;   vf_read<1>(fb, vb);  VF_WAIT(8); vf_mma(o[0], fa, pa0, pa1, pa2, pa3); SBAR();
;   vf_read<2>(fa, vb);  VF_WAIT(8); vf_mma(o[1], fb, pa0, pa1, pa2, pa3); SBAR();
;   vf_read<3>(fb, vb);  VF_WAIT(8); vf_mma(o[2], fa, pa0, pa1, pa2, pa3); SBAR();
;   vf_read<0>(fa, vb2); VF_WAIT(8); vf_mma(o[3], fb, pa0, pa1, pa2, pa3); SBAR();
;   vf_read<1>(fb, vb2); VF_WAIT(8); vf_mma(o[4], fa, pa0, pa1, pa2, pa3); SBAR();
;   vf_read<2>(fa, vb2); VF_WAIT(8); vf_mma(o[5], fb, pa0, pa1, pa2, pa3); SBAR();
;   vf_read<3>(fb, vb2); VF_WAIT(8); vf_mma(o[6], fa, pa0, pa1, pa2, pa3); SBAR();
;   VF_WAIT(0); vf_mma(o[7], fb, pa0, pa1, pa2, pa3);
; }
; template <int mode> ...
;     ...
;     if (more) A_WAITBAR(6); else A_WAITBAR(0);
;     if (more) DMA_V(j + 2, s2);
;     pv8(o, vb0 + s0 * 32768, pa0, pa1, pa2, pa3);
;     if (more) A_WAITBAR(6); else A_WAITBAR(0);
.LBB0_363:
	v_lshl_add_u32 v220, s11, 15, v223
	ds_read_b64_tr_b16 v[144:145], v220 offset:0
	ds_read_b64_tr_b16 v[146:147], v220 offset:0x800
	ds_read_b64_tr_b16 v[148:149], v220 offset:0x1000
	ds_read_b64_tr_b16 v[150:151], v220 offset:0x1800
	ds_read_b64_tr_b16 v[152:153], v220 offset:0x2000
	ds_read_b64_tr_b16 v[154:155], v220 offset:0x2800
	ds_read_b64_tr_b16 v[156:157], v220 offset:0x3000
	ds_read_b64_tr_b16 v[158:159], v220 offset:0x3800
	ds_read_b64_tr_b16 v[194:195], v220 offset:0x200
	ds_read_b64_tr_b16 v[196:197], v220 offset:0xa00
	ds_read_b64_tr_b16 v[214:215], v220 offset:0x1200
	ds_read_b64_tr_b16 v[216:217], v220 offset:0x1a00
	ds_read_b64_tr_b16 v[228:229], v220 offset:0x2200
	ds_read_b64_tr_b16 v[230:231], v220 offset:0x2a00
	ds_read_b64_tr_b16 v[232:233], v220 offset:0x3200
	ds_read_b64_tr_b16 v[234:235], v220 offset:0x3a00
	s_waitcnt lgkmcnt(8)
	v_add_u32_e32 v221, 0x4000, v220
	v_mfma_f32_32x32x16_bf16 v[112:127], v[128:131], v[144:147], v[112:127]
	v_mfma_f32_32x32x16_bf16 v[112:127], v[132:135], v[148:151], v[112:127]
	v_mfma_f32_32x32x16_bf16 v[112:127], v[136:139], v[152:155], v[112:127]
	v_mfma_f32_32x32x16_bf16 v[112:127], v[140:143], v[156:159], v[112:127]
	ds_read_b64_tr_b16 v[144:145], v220 offset:0x400
	ds_read_b64_tr_b16 v[146:147], v220 offset:0xc00
	ds_read_b64_tr_b16 v[148:149], v220 offset:0x1400
	ds_read_b64_tr_b16 v[150:151], v220 offset:0x1c00
	ds_read_b64_tr_b16 v[152:153], v220 offset:0x2400
	ds_read_b64_tr_b16 v[154:155], v220 offset:0x2c00
	ds_read_b64_tr_b16 v[156:157], v220 offset:0x3400
	ds_read_b64_tr_b16 v[158:159], v220 offset:0x3c00
	s_waitcnt lgkmcnt(8)
	v_mfma_f32_32x32x16_bf16 v[96:111], v[128:131], v[194:197], v[96:111]
	v_mfma_f32_32x32x16_bf16 v[96:111], v[132:135], v[214:217], v[96:111]
	v_mfma_f32_32x32x16_bf16 v[96:111], v[136:139], v[228:231], v[96:111]
	v_mfma_f32_32x32x16_bf16 v[96:111], v[140:143], v[232:235], v[96:111]
	ds_read_b64_tr_b16 v[194:195], v220 offset:0x600
	ds_read_b64_tr_b16 v[196:197], v220 offset:0xe00
	ds_read_b64_tr_b16 v[214:215], v220 offset:0x1600
	ds_read_b64_tr_b16 v[216:217], v220 offset:0x1e00
	ds_read_b64_tr_b16 v[228:229], v220 offset:0x2600
	ds_read_b64_tr_b16 v[230:231], v220 offset:0x2e00
	ds_read_b64_tr_b16 v[232:233], v220 offset:0x3600
	ds_read_b64_tr_b16 v[234:235], v220 offset:0x3e00
	s_waitcnt lgkmcnt(8)
	v_mfma_f32_32x32x16_bf16 v[80:95], v[128:131], v[144:147], v[80:95]
	v_mfma_f32_32x32x16_bf16 v[80:95], v[132:135], v[148:151], v[80:95]
	v_mfma_f32_32x32x16_bf16 v[80:95], v[136:139], v[152:155], v[80:95]
	v_mfma_f32_32x32x16_bf16 v[80:95], v[140:143], v[156:159], v[80:95]
	ds_read_b64_tr_b16 v[144:145], v221 offset:0
	ds_read_b64_tr_b16 v[146:147], v221 offset:0x800
	ds_read_b64_tr_b16 v[148:149], v221 offset:0x1000
	ds_read_b64_tr_b16 v[150:151], v221 offset:0x1800
	ds_read_b64_tr_b16 v[152:153], v221 offset:0x2000
	ds_read_b64_tr_b16 v[154:155], v221 offset:0x2800
	ds_read_b64_tr_b16 v[156:157], v221 offset:0x3000
	ds_read_b64_tr_b16 v[158:159], v221 offset:0x3800
	s_waitcnt lgkmcnt(8)
	v_mfma_f32_32x32x16_bf16 v[64:79], v[128:131], v[194:197], v[64:79]
	v_mfma_f32_32x32x16_bf16 v[64:79], v[132:135], v[214:217], v[64:79]
	v_mfma_f32_32x32x16_bf16 v[64:79], v[136:139], v[228:231], v[64:79]
	v_mfma_f32_32x32x16_bf16 v[64:79], v[140:143], v[232:235], v[64:79]
	ds_read_b64_tr_b16 v[194:195], v221 offset:0x200
	ds_read_b64_tr_b16 v[196:197], v221 offset:0xa00
	ds_read_b64_tr_b16 v[214:215], v221 offset:0x1200
	ds_read_b64_tr_b16 v[216:217], v221 offset:0x1a00
	ds_read_b64_tr_b16 v[228:229], v221 offset:0x2200
	ds_read_b64_tr_b16 v[230:231], v221 offset:0x2a00
	ds_read_b64_tr_b16 v[232:233], v221 offset:0x3200
	ds_read_b64_tr_b16 v[234:235], v221 offset:0x3a00
	s_cbranch_vccnz .Lp0_nodma
	s_lshl_b32 s12, s9, 15
	s_add_i32 s12, s12, s7
	s_mov_b32 s13, m0
	s_mov_b32 m0, s12
	s_nop 0
	global_load_lds_dwordx4 v204, s[38:39]
	s_add_i32 s24, s12, 0x400
	s_mov_b32 m0, s24
	s_nop 0
	global_load_lds_dwordx4 v206, s[38:39]
	s_add_i32 s24, s12, 0x800
	s_mov_b32 m0, s24
	s_nop 0
	global_load_lds_dwordx4 v208, s[38:39]
	s_add_i32 s24, s12, 0xc00
	s_mov_b32 m0, s24
	s_nop 0
	global_load_lds_dwordx4 v210, s[38:39]
	s_mov_b32 m0, s13
.Lp0_nodma:
	s_waitcnt lgkmcnt(8)
	v_mfma_f32_32x32x16_bf16 v[48:63], v[128:131], v[144:147], v[48:63]
	v_mfma_f32_32x32x16_bf16 v[48:63], v[132:135], v[148:151], v[48:63]
	v_mfma_f32_32x32x16_bf16 v[48:63], v[136:139], v[152:155], v[48:63]
	v_mfma_f32_32x32x16_bf16 v[48:63], v[140:143], v[156:159], v[48:63]
	ds_read_b64_tr_b16 v[144:145], v221 offset:0x400
	ds_read_b64_tr_b16 v[146:147], v221 offset:0xc00
	ds_read_b64_tr_b16 v[148:149], v221 offset:0x1400
	ds_read_b64_tr_b16 v[150:151], v221 offset:0x1c00
	ds_read_b64_tr_b16 v[152:153], v221 offset:0x2400
	ds_read_b64_tr_b16 v[154:155], v221 offset:0x2c00
	ds_read_b64_tr_b16 v[156:157], v221 offset:0x3400
	ds_read_b64_tr_b16 v[158:159], v221 offset:0x3c00
	s_waitcnt lgkmcnt(8)
	v_mfma_f32_32x32x16_bf16 v[32:47], v[128:131], v[194:197], v[32:47]
	v_mfma_f32_32x32x16_bf16 v[32:47], v[132:135], v[214:217], v[32:47]
	v_mfma_f32_32x32x16_bf16 v[32:47], v[136:139], v[228:231], v[32:47]
	v_mfma_f32_32x32x16_bf16 v[32:47], v[140:143], v[232:235], v[32:47]
	ds_read_b64_tr_b16 v[194:195], v221 offset:0x600
	ds_read_b64_tr_b16 v[196:197], v221 offset:0xe00
	ds_read_b64_tr_b16 v[214:215], v221 offset:0x1600
	ds_read_b64_tr_b16 v[216:217], v221 offset:0x1e00
	ds_read_b64_tr_b16 v[228:229], v221 offset:0x2600
	ds_read_b64_tr_b16 v[230:231], v221 offset:0x2e00
	ds_read_b64_tr_b16 v[232:233], v221 offset:0x3600
	ds_read_b64_tr_b16 v[234:235], v221 offset:0x3e00
	s_waitcnt lgkmcnt(8)
	v_mfma_f32_32x32x16_bf16 v[16:31], v[128:131], v[144:147], v[16:31]
	v_mfma_f32_32x32x16_bf16 v[16:31], v[132:135], v[148:151], v[16:31]
	v_mfma_f32_32x32x16_bf16 v[16:31], v[136:139], v[152:155], v[16:31]
	v_mfma_f32_32x32x16_bf16 v[16:31], v[140:143], v[156:159], v[16:31]
	s_waitcnt lgkmcnt(0)
	v_mfma_f32_32x32x16_bf16 v[0:15], v[128:131], v[194:197], v[0:15]
	s_and_b64 vcc, exec, s[90:91]
	v_mfma_f32_32x32x16_bf16 v[0:15], v[132:135], v[214:217], v[0:15]
	v_mfma_f32_32x32x16_bf16 v[0:15], v[136:139], v[228:231], v[0:15]
	v_mfma_f32_32x32x16_bf16 v[0:15], v[140:143], v[232:235], v[0:15]
	s_cbranch_vccnz .Lm0_ybar0
	s_waitcnt vmcnt(6) lgkmcnt(0)
	s_barrier

; #define SBAR() __builtin_amdgcn_sched_barrier(0)
; #define VF_WAIT(N) do { asm volatile("s_waitcnt lgkmcnt(" #N ")" ::: "memory"); SBAR(); } while (0)
; #define A_WAITBAR(N) asm volatile("s_waitcnt vmcnt(" #N ") lgkmcnt(0) ; A256BAR\n\ts_barrier" ::: "memory")
; #define DMA_V(t, sl) do { const char* b_ = Vb + (size_t)(t) * TSTRIDE; const unsigned d_ = RFL(vdst + (sl) * 32768); glds16(b_ + voff[0], d_); glds16(b_ + voff[1], d_ + 1024); glds16(b_ + voff[2], d_ + 2048); glds16(b_ + voff[3], d_ + 3072); } while (0)
; __device__ __forceinline__ void pv8(f32x16* o, int vb, bf16x8 pa0, bf16x8 pa1, bf16x8 pa2, bf16x8 pa3) {
;   VFrag fa, fb; const int vb2 = vb + 16384;
;   vf_read<0>(fa, vb);
;   vf_read<1>(fb, vb);  VF_WAIT(8); vf_mma(o[0], fa, pa0, pa1, pa2, pa3); SBAR();
;   vf_read<2>(fa, vb);  VF_WAIT(8); vf_mma(o[1], fb, pa0, pa1, pa2, pa3); SBAR();
;   vf_read<3>(fb, vb);  VF_WAIT(8); vf_mma(o[2], fa, pa0, pa1, pa2, pa3); SBAR();
;   vf_read<0>(fa, vb2); VF_WAIT(8); vf_mma(o[3], fb, pa0, pa1, pa2, pa3); SBAR();
;   vf_read<1>(fb, vb2); VF_WAIT(8); vf_mma(o[4], fa, pa0, pa1, pa2, pa3); SBAR();
;   vf_read<2>(fa, vb2); VF_WAIT(8); vf_mma(o[5], fb, pa0, pa1, pa2, pa3); SBAR();
;   vf_read<3>(fb, vb2); VF_WAIT(8); vf_mma(o[6], fa, pa0, pa1, pa2, pa3); SBAR();
;   VF_WAIT(0); vf_mma(o[7], fb, pa0, pa1, pa2, pa3);
; }
; template <int mode> ...
;     ...
;     if (more) A_WAITBAR(6); else A_WAITBAR(0);
;     if (more) DMA_V(j + 2, s2);
;     pv8(o, vb0 + s0 * 32768, pa0, pa1, pa2, pa3);
;     if (more) A_WAITBAR(6); else A_WAITBAR(0);
.LBB0_396:
	v_lshl_add_u32 v231, s10, 15, v226
	ds_read_b64_tr_b16 v[144:145], v231 offset:0
	ds_read_b64_tr_b16 v[146:147], v231 offset:0x800
	ds_read_b64_tr_b16 v[148:149], v231 offset:0x1000
	ds_read_b64_tr_b16 v[150:151], v231 offset:0x1800
	ds_read_b64_tr_b16 v[152:153], v231 offset:0x2000
	ds_read_b64_tr_b16 v[154:155], v231 offset:0x2800
	ds_read_b64_tr_b16 v[156:157], v231 offset:0x3000
	ds_read_b64_tr_b16 v[158:159], v231 offset:0x3800
	ds_read_b64_tr_b16 v[194:195], v231 offset:0x200
	ds_read_b64_tr_b16 v[196:197], v231 offset:0xa00
	ds_read_b64_tr_b16 v[214:215], v231 offset:0x1200
	ds_read_b64_tr_b16 v[216:217], v231 offset:0x1a00
	ds_read_b64_tr_b16 v[220:221], v231 offset:0x2200
	ds_read_b64_tr_b16 v[222:223], v231 offset:0x2a00
	ds_read_b64_tr_b16 v[232:233], v231 offset:0x3200
	ds_read_b64_tr_b16 v[234:235], v231 offset:0x3a00
	s_waitcnt lgkmcnt(8)
	v_add_u32_e32 v236, 0x4000, v231
	v_mfma_f32_32x32x16_bf16 v[16:31], v[128:131], v[144:147], v[16:31]
	v_mfma_f32_32x32x16_bf16 v[16:31], v[132:135], v[148:151], v[16:31]
	v_mfma_f32_32x32x16_bf16 v[16:31], v[136:139], v[152:155], v[16:31]
	v_mfma_f32_32x32x16_bf16 v[16:31], v[140:143], v[156:159], v[16:31]
	ds_read_b64_tr_b16 v[144:145], v231 offset:0x400
	ds_read_b64_tr_b16 v[146:147], v231 offset:0xc00
	ds_read_b64_tr_b16 v[148:149], v231 offset:0x1400
	ds_read_b64_tr_b16 v[150:151], v231 offset:0x1c00
	ds_read_b64_tr_b16 v[152:153], v231 offset:0x2400
	ds_read_b64_tr_b16 v[154:155], v231 offset:0x2c00
	ds_read_b64_tr_b16 v[156:157], v231 offset:0x3400
	ds_read_b64_tr_b16 v[158:159], v231 offset:0x3c00
	s_waitcnt lgkmcnt(8)
	v_mfma_f32_32x32x16_bf16 v[32:47], v[128:131], v[194:197], v[32:47]
	v_mfma_f32_32x32x16_bf16 v[32:47], v[132:135], v[214:217], v[32:47]
	v_mfma_f32_32x32x16_bf16 v[32:47], v[136:139], v[220:223], v[32:47]
	v_mfma_f32_32x32x16_bf16 v[32:47], v[140:143], v[232:235], v[32:47]
	ds_read_b64_tr_b16 v[194:195], v231 offset:0x600
	ds_read_b64_tr_b16 v[196:197], v231 offset:0xe00
	ds_read_b64_tr_b16 v[214:215], v231 offset:0x1600
	ds_read_b64_tr_b16 v[216:217], v231 offset:0x1e00
	ds_read_b64_tr_b16 v[220:221], v231 offset:0x2600
	ds_read_b64_tr_b16 v[222:223], v231 offset:0x2e00
	ds_read_b64_tr_b16 v[232:233], v231 offset:0x3600
	ds_read_b64_tr_b16 v[234:235], v231 offset:0x3e00
	s_waitcnt lgkmcnt(8)
	v_mfma_f32_32x32x16_bf16 v[96:111], v[128:131], v[144:147], v[96:111]
	v_mfma_f32_32x32x16_bf16 v[96:111], v[132:135], v[148:151], v[96:111]
	v_mfma_f32_32x32x16_bf16 v[96:111], v[136:139], v[152:155], v[96:111]
	v_mfma_f32_32x32x16_bf16 v[96:111], v[140:143], v[156:159], v[96:111]
	ds_read_b64_tr_b16 v[144:145], v236 offset:0
	ds_read_b64_tr_b16 v[146:147], v236 offset:0x800
	ds_read_b64_tr_b16 v[148:149], v236 offset:0x1000
	ds_read_b64_tr_b16 v[150:151], v236 offset:0x1800
	ds_read_b64_tr_b16 v[152:153], v236 offset:0x2000
	ds_read_b64_tr_b16 v[154:155], v236 offset:0x2800
	ds_read_b64_tr_b16 v[156:157], v236 offset:0x3000
	ds_read_b64_tr_b16 v[158:159], v236 offset:0x3800
	s_waitcnt lgkmcnt(8)
	v_mfma_f32_32x32x16_bf16 v[112:127], v[128:131], v[194:197], v[112:127]
	v_mfma_f32_32x32x16_bf16 v[112:127], v[132:135], v[214:217], v[112:127]
	v_mfma_f32_32x32x16_bf16 v[112:127], v[136:139], v[220:223], v[112:127]
	v_mfma_f32_32x32x16_bf16 v[112:127], v[140:143], v[232:235], v[112:127]
	ds_read_b64_tr_b16 v[194:195], v236 offset:0x200
	ds_read_b64_tr_b16 v[196:197], v236 offset:0xa00
	ds_read_b64_tr_b16 v[214:215], v236 offset:0x1200
	ds_read_b64_tr_b16 v[216:217], v236 offset:0x1a00
	ds_read_b64_tr_b16 v[220:221], v236 offset:0x2200
	ds_read_b64_tr_b16 v[222:223], v236 offset:0x2a00
	ds_read_b64_tr_b16 v[232:233], v236 offset:0x3200
	ds_read_b64_tr_b16 v[234:235], v236 offset:0x3a00
	s_cbranch_vccnz .Lp1_nodma
	s_lshl_b32 s11, s7, 15
	s_add_i32 s11, s11, s5
	s_mov_b32 s12, m0
	s_mov_b32 m0, s11
	s_nop 0
	global_load_lds_dwordx4 v204, s[60:61]
	s_add_i32 s13, s11, 0x400
	s_mov_b32 m0, s13
	s_nop 0
	global_load_lds_dwordx4 v206, s[60:61]
	s_add_i32 s13, s11, 0x800
	s_mov_b32 m0, s13
	s_nop 0
	global_load_lds_dwordx4 v208, s[60:61]
	s_add_i32 s13, s11, 0xc00
	s_mov_b32 m0, s13
	s_nop 0
	global_load_lds_dwordx4 v210, s[60:61]
	s_mov_b32 m0, s12
.Lp1_nodma:
	s_waitcnt lgkmcnt(8)
	v_mfma_f32_32x32x16_bf16 v[64:79], v[128:131], v[144:147], v[64:79]
	v_mfma_f32_32x32x16_bf16 v[64:79], v[132:135], v[148:151], v[64:79]
	v_mfma_f32_32x32x16_bf16 v[64:79], v[136:139], v[152:155], v[64:79]
	v_mfma_f32_32x32x16_bf16 v[64:79], v[140:143], v[156:159], v[64:79]
	ds_read_b64_tr_b16 v[144:145], v236 offset:0x400
	ds_read_b64_tr_b16 v[146:147], v236 offset:0xc00
	ds_read_b64_tr_b16 v[148:149], v236 offset:0x1400
	ds_read_b64_tr_b16 v[150:151], v236 offset:0x1c00
	ds_read_b64_tr_b16 v[152:153], v236 offset:0x2400
	ds_read_b64_tr_b16 v[154:155], v236 offset:0x2c00
	ds_read_b64_tr_b16 v[156:157], v236 offset:0x3400
	ds_read_b64_tr_b16 v[158:159], v236 offset:0x3c00
	s_waitcnt lgkmcnt(8)
	v_mfma_f32_32x32x16_bf16 v[48:63], v[128:131], v[194:197], v[48:63]
	v_mfma_f32_32x32x16_bf16 v[48:63], v[132:135], v[214:217], v[48:63]
	v_mfma_f32_32x32x16_bf16 v[48:63], v[136:139], v[220:223], v[48:63]
	v_mfma_f32_32x32x16_bf16 v[48:63], v[140:143], v[232:235], v[48:63]
	ds_read_b64_tr_b16 v[194:195], v236 offset:0x600
	ds_read_b64_tr_b16 v[196:197], v236 offset:0xe00
	ds_read_b64_tr_b16 v[214:215], v236 offset:0x1600
	ds_read_b64_tr_b16 v[216:217], v236 offset:0x1e00
	ds_read_b64_tr_b16 v[220:221], v236 offset:0x2600
	ds_read_b64_tr_b16 v[222:223], v236 offset:0x2e00
	ds_read_b64_tr_b16 v[232:233], v236 offset:0x3600
	ds_read_b64_tr_b16 v[234:235], v236 offset:0x3e00
	s_waitcnt lgkmcnt(8)
	v_mfma_f32_32x32x16_bf16 v[0:15], v[128:131], v[144:147], v[0:15]
	v_mfma_f32_32x32x16_bf16 v[0:15], v[132:135], v[148:151], v[0:15]
	v_mfma_f32_32x32x16_bf16 v[0:15], v[136:139], v[152:155], v[0:15]
	v_mfma_f32_32x32x16_bf16 v[0:15], v[140:143], v[156:159], v[0:15]
	s_waitcnt lgkmcnt(0)
	v_mfma_f32_32x32x16_bf16 v[80:95], v[128:131], v[194:197], v[80:95]
	s_and_b64 vcc, exec, s[50:51]
	v_mfma_f32_32x32x16_bf16 v[80:95], v[132:135], v[214:217], v[80:95]
	v_mfma_f32_32x32x16_bf16 v[80:95], v[136:139], v[220:223], v[80:95]
	v_mfma_f32_32x32x16_bf16 v[80:95], v[140:143], v[232:235], v[80:95]
	s_cbranch_vccnz .Lm1_ybar0
	s_waitcnt vmcnt(6) lgkmcnt(0)
	s_barrier
